# gate: the u rows and biases for both epilogue halves are loaded right after the pre-MFMA barrier (latency overlaps weight loads and MFMAs); epilogue halves copy registers, obsolete waits dropped
# speedup vs baseline: 1.0028x; 1.0028x over previous
.LBB0_792:
	s_or_b64 exec, exec, s[38:39]
	v_lshl_add_u64 v[110:111], s[42:43], 0, v[70:71]
	v_add_co_u32_e32 v0, vcc, 0x3600000, v110
	ds_write_b128 v130, v[24:27] offset:60928
	s_nop 0
	v_addc_co_u32_e32 v1, vcc, 0, v111, vcc
	v_add_co_u32_e32 v4, vcc, 0x3601000, v110
	s_waitcnt lgkmcnt(0)
	s_nop 0
	v_addc_co_u32_e32 v5, vcc, 0, v111, vcc
	s_barrier
	s_and_saveexec_b64 s[100:101], s[22:23]
	global_load_dword v200, v[66:67], off offset:-64
	v_lshl_add_u64 v[248:249], s[42:43], 0, v[94:95]
	global_load_dwordx2 v[202:203], v[248:249], off offset:-128
	global_load_dwordx2 v[204:205], v[248:249], off offset:-96
	global_load_dwordx2 v[206:207], v[248:249], off offset:-64
	global_load_dwordx2 v[208:209], v[248:249], off offset:-32
	global_load_dwordx2 v[210:211], v[248:249], off
	global_load_dwordx2 v[212:213], v[248:249], off offset:32
	global_load_dwordx2 v[214:215], v[248:249], off offset:64
	global_load_dwordx2 v[216:217], v[248:249], off offset:96
	s_or_b64 exec, exec, s[100:101]
	s_and_saveexec_b64 s[100:101], s[24:25]
	global_load_dword v201, v[66:67], off
	v_lshl_add_u64 v[250:251], s[42:43], 0, v[108:109]
	global_load_dwordx2 v[218:219], v[250:251], off offset:-128
	global_load_dwordx2 v[220:221], v[250:251], off offset:-96
	global_load_dwordx2 v[222:223], v[250:251], off offset:-64
	global_load_dwordx2 v[224:225], v[250:251], off offset:-32
	global_load_dwordx2 v[226:227], v[250:251], off
	global_load_dwordx2 v[228:229], v[250:251], off offset:32
	global_load_dwordx2 v[230:231], v[250:251], off offset:64
	global_load_dwordx2 v[232:233], v[250:251], off offset:96
	s_or_b64 exec, exec, s[100:101]
	global_load_dwordx4 v[0:3], v[0:1], off
	s_andn2_b64 vcc, exec, s[54:55]
	global_load_dwordx4 v[132:135], v[4:5], off
	ds_read_b64_tr_b16 v[4:5], v122
	ds_read_b64_tr_b16 v[6:7], v122 offset:2176
	ds_read_b64_tr_b16 v[10:11], v122 offset:2208
	ds_read_b64_tr_b16 v[8:9], v122 offset:32
	ds_read_b64_tr_b16 v[12:13], v122 offset:64
	ds_read_b64_tr_b16 v[16:17], v122 offset:96
	ds_read_b64_tr_b16 v[14:15], v122 offset:2240
	ds_read_b64_tr_b16 v[18:19], v122 offset:2272
	ds_read_b64_tr_b16 v[136:137], v122 offset:128
	ds_read_b64_tr_b16 v[138:139], v122 offset:2304
	ds_read_b64_tr_b16 v[142:143], v122 offset:2336
	ds_read_b64_tr_b16 v[140:141], v122 offset:160
	ds_read_b64_tr_b16 v[144:145], v122 offset:192
	ds_read_b64_tr_b16 v[148:149], v122 offset:224
	ds_read_b64_tr_b16 v[146:147], v122 offset:2368
	ds_read_b64_tr_b16 v[150:151], v122 offset:2400
	s_waitcnt vmcnt(1) lgkmcnt(14)
	v_mfma_f32_16x16x32_bf16 v[40:43], v[4:7], v[0:3], 0
	s_waitcnt lgkmcnt(12)
	v_mfma_f32_16x16x32_bf16 v[36:39], v[8:11], v[0:3], 0
	s_waitcnt lgkmcnt(9)
	v_mfma_f32_16x16x32_bf16 v[44:47], v[12:15], v[0:3], 0
	s_waitcnt lgkmcnt(8)
	v_mfma_f32_16x16x32_bf16 v[48:51], v[16:19], v[0:3], 0
	s_waitcnt lgkmcnt(6)
	v_mfma_f32_16x16x32_bf16 v[60:63], v[136:139], v[0:3], 0
	s_waitcnt lgkmcnt(4)
	v_mfma_f32_16x16x32_bf16 v[56:59], v[140:143], v[0:3], 0
	s_waitcnt lgkmcnt(1)
	v_mfma_f32_16x16x32_bf16 v[52:55], v[144:147], v[0:3], 0
	s_waitcnt lgkmcnt(0)
	v_mfma_f32_16x16x32_bf16 v[32:35], v[148:151], v[0:3], 0
	s_waitcnt vmcnt(0)
	v_mfma_f32_16x16x32_bf16 v[28:31], v[4:7], v[132:135], 0
	v_mfma_f32_16x16x32_bf16 v[24:27], v[8:11], v[132:135], 0
	v_mfma_f32_16x16x32_bf16 v[20:23], v[12:15], v[132:135], 0
	v_mfma_f32_16x16x32_bf16 v[16:19], v[16:19], v[132:135], 0
	v_mfma_f32_16x16x32_bf16 v[12:15], v[136:139], v[132:135], 0
	v_mfma_f32_16x16x32_bf16 v[8:11], v[140:143], v[132:135], 0
	v_mfma_f32_16x16x32_bf16 v[4:7], v[144:147], v[132:135], 0
	v_mfma_f32_16x16x32_bf16 v[0:3], v[148:151], v[132:135], 0
	s_cbranch_vccnz .LBB0_794
	v_add_co_u32_e32 v132, vcc, 0x3600000, v110
	s_nop 1
	v_addc_co_u32_e32 v133, vcc, 0, v111, vcc
	v_add_co_u32_e32 v136, vcc, 0x3601000, v110
	global_load_dwordx4 v[132:135], v[132:133], off offset:64
	s_nop 0
	v_addc_co_u32_e32 v137, vcc, 0, v111, vcc
	global_load_dwordx4 v[136:139], v[136:137], off offset:64
	ds_read_b64_tr_b16 v[140:141], v122 offset:17408
	ds_read_b64_tr_b16 v[142:143], v122 offset:19584
	ds_read_b64_tr_b16 v[146:147], v122 offset:19616
	ds_read_b64_tr_b16 v[144:145], v122 offset:17440
	ds_read_b64_tr_b16 v[148:149], v122 offset:17472
	ds_read_b64_tr_b16 v[152:153], v122 offset:17504
	ds_read_b64_tr_b16 v[150:151], v122 offset:19648
	ds_read_b64_tr_b16 v[154:155], v122 offset:19680
	ds_read_b64_tr_b16 v[156:157], v122 offset:17536
	ds_read_b64_tr_b16 v[158:159], v122 offset:19712
	ds_read_b64_tr_b16 v[162:163], v122 offset:19744
	ds_read_b64_tr_b16 v[160:161], v122 offset:17568
	ds_read_b64_tr_b16 v[164:165], v122 offset:17600
	ds_read_b64_tr_b16 v[168:169], v122 offset:17632
	ds_read_b64_tr_b16 v[166:167], v122 offset:19776
	ds_read_b64_tr_b16 v[170:171], v122 offset:19808
	s_waitcnt vmcnt(1) lgkmcnt(14)
	v_mfma_f32_16x16x32_bf16 v[40:43], v[140:143], v[132:135], v[40:43]
	s_waitcnt lgkmcnt(12)
	v_mfma_f32_16x16x32_bf16 v[36:39], v[144:147], v[132:135], v[36:39]
	s_waitcnt lgkmcnt(9)
	v_mfma_f32_16x16x32_bf16 v[44:47], v[148:151], v[132:135], v[44:47]
	s_waitcnt lgkmcnt(8)
	v_mfma_f32_16x16x32_bf16 v[48:51], v[152:155], v[132:135], v[48:51]
	s_waitcnt lgkmcnt(6)
	v_mfma_f32_16x16x32_bf16 v[60:63], v[156:159], v[132:135], v[60:63]
	s_waitcnt lgkmcnt(4)
	v_mfma_f32_16x16x32_bf16 v[56:59], v[160:163], v[132:135], v[56:59]
	s_waitcnt lgkmcnt(1)
	v_mfma_f32_16x16x32_bf16 v[52:55], v[164:167], v[132:135], v[52:55]
	s_waitcnt lgkmcnt(0)
	v_mfma_f32_16x16x32_bf16 v[32:35], v[168:171], v[132:135], v[32:35]
	s_waitcnt vmcnt(0)
	v_mfma_f32_16x16x32_bf16 v[28:31], v[140:143], v[136:139], v[28:31]
	v_mfma_f32_16x16x32_bf16 v[24:27], v[144:147], v[136:139], v[24:27]
	v_mfma_f32_16x16x32_bf16 v[20:23], v[148:151], v[136:139], v[20:23]
	v_mfma_f32_16x16x32_bf16 v[16:19], v[152:155], v[136:139], v[16:19]
	v_mfma_f32_16x16x32_bf16 v[12:15], v[156:159], v[136:139], v[12:15]
	v_mfma_f32_16x16x32_bf16 v[8:11], v[160:163], v[136:139], v[8:11]
	v_mfma_f32_16x16x32_bf16 v[4:7], v[164:167], v[136:139], v[4:7]
	v_mfma_f32_16x16x32_bf16 v[0:3], v[168:171], v[136:139], v[0:3]

.LBB0_797:
	s_waitcnt vmcnt(0)
	v_mov_b32_e32 v110, v200
	v_lshl_add_u64 v[132:133], s[42:43], 0, v[94:95]
	v_mov_b32_e32 v134, v202
	v_mov_b32_e32 v135, v203
	v_mov_b32_e32 v136, v204
	v_mov_b32_e32 v137, v205
	v_mov_b32_e32 v138, v206
	v_mov_b32_e32 v139, v207
	v_mov_b32_e32 v140, v208
	v_mov_b32_e32 v141, v209
	v_mov_b32_e32 v142, v210
	v_mov_b32_e32 v143, v211
	v_mov_b32_e32 v144, v212
	v_mov_b32_e32 v145, v213
	v_mov_b32_e32 v146, v214
	v_mov_b32_e32 v147, v215
	v_mov_b32_e32 v148, v216
	v_mov_b32_e32 v149, v217
	s_waitcnt vmcnt(7)
	v_lshlrev_b32_e32 v150, 16, v134
	v_and_b32_e32 v151, 0xffff0000, v134
	v_lshlrev_b32_e32 v134, 16, v135
	v_and_b32_e32 v135, 0xffff0000, v135
	s_waitcnt vmcnt(6)
	v_lshlrev_b32_e32 v152, 16, v136
	v_pk_add_f32 v[42:43], v[42:43], v[110:111] op_sel_hi:[1,0]
	v_pk_add_f32 v[40:41], v[40:41], v[110:111] op_sel_hi:[1,0]
	v_pk_add_f32 v[38:39], v[38:39], v[110:111] op_sel_hi:[1,0]
	v_pk_add_f32 v[36:37], v[36:37], v[110:111] op_sel_hi:[1,0]
	v_and_b32_e32 v153, 0xffff0000, v136
	v_lshlrev_b32_e32 v136, 16, v137
	v_and_b32_e32 v137, 0xffff0000, v137
	v_pk_add_f32 v[46:47], v[46:47], v[110:111] op_sel_hi:[1,0]
	v_pk_add_f32 v[44:45], v[44:45], v[110:111] op_sel_hi:[1,0]
	v_pk_add_f32 v[50:51], v[50:51], v[110:111] op_sel_hi:[1,0]
	v_pk_add_f32 v[48:49], v[48:49], v[110:111] op_sel_hi:[1,0]
	v_pk_add_f32 v[62:63], v[62:63], v[110:111] op_sel_hi:[1,0]
	v_pk_add_f32 v[60:61], v[60:61], v[110:111] op_sel_hi:[1,0]
	v_pk_add_f32 v[58:59], v[58:59], v[110:111] op_sel_hi:[1,0]
	v_pk_add_f32 v[56:57], v[56:57], v[110:111] op_sel_hi:[1,0]
	s_waitcnt vmcnt(5)
	v_lshlrev_b32_e32 v154, 16, v138
	v_and_b32_e32 v155, 0xffff0000, v138
	v_lshlrev_b32_e32 v138, 16, v139
	v_and_b32_e32 v139, 0xffff0000, v139
	s_waitcnt vmcnt(4)
	v_lshlrev_b32_e32 v156, 16, v140
	v_and_b32_e32 v157, 0xffff0000, v140
	v_lshlrev_b32_e32 v140, 16, v141
	v_and_b32_e32 v141, 0xffff0000, v141
	s_waitcnt vmcnt(3)
	v_lshlrev_b32_e32 v158, 16, v142
	v_and_b32_e32 v159, 0xffff0000, v142
	v_lshlrev_b32_e32 v142, 16, v143
	v_and_b32_e32 v143, 0xffff0000, v143
	s_waitcnt vmcnt(2)
	v_lshlrev_b32_e32 v160, 16, v144
	v_and_b32_e32 v161, 0xffff0000, v144
	v_lshlrev_b32_e32 v144, 16, v145
	v_and_b32_e32 v145, 0xffff0000, v145
	v_pk_mul_f32 v[40:41], v[40:41], v[150:151]
	v_pk_mul_f32 v[42:43], v[42:43], v[134:135]
	v_pk_mul_f32 v[36:37], v[36:37], v[152:153]
	v_pk_mul_f32 v[38:39], v[38:39], v[136:137]
	v_pk_mul_f32 v[44:45], v[44:45], v[154:155]
	v_pk_mul_f32 v[46:47], v[46:47], v[138:139]
	v_pk_mul_f32 v[48:49], v[48:49], v[156:157]
	v_pk_mul_f32 v[50:51], v[50:51], v[140:141]
	v_pk_mul_f32 v[60:61], v[60:61], v[158:159]
	v_pk_mul_f32 v[62:63], v[62:63], v[142:143]
	v_pk_mul_f32 v[56:57], v[56:57], v[160:161]
	v_pk_mul_f32 v[58:59], v[58:59], v[144:145]
	v_cvt_pk_bf16_f32 v40, v40, v41
	v_cvt_pk_bf16_f32 v41, v42, v43
	v_cvt_pk_bf16_f32 v36, v36, v37
	v_cvt_pk_bf16_f32 v37, v38, v39
	v_cvt_pk_bf16_f32 v38, v44, v45
	v_cvt_pk_bf16_f32 v39, v46, v47
	v_cvt_pk_bf16_f32 v42, v48, v49
	v_cvt_pk_bf16_f32 v43, v50, v51
	v_cvt_pk_bf16_f32 v44, v60, v61
	v_cvt_pk_bf16_f32 v45, v62, v63
	v_cvt_pk_bf16_f32 v46, v56, v57
	v_cvt_pk_bf16_f32 v47, v58, v59
	global_store_dwordx2 v[132:133], v[40:41], off offset:-128
	global_store_dwordx2 v[132:133], v[36:37], off offset:-96
	global_store_dwordx2 v[132:133], v[38:39], off offset:-64
	global_store_dwordx2 v[132:133], v[42:43], off offset:-32
	global_store_dwordx2 v[132:133], v[44:45], off
	global_store_dwordx2 v[132:133], v[46:47], off offset:32
	v_pk_add_f32 v[32:33], v[32:33], v[110:111] op_sel_hi:[1,0]
	s_waitcnt vmcnt(6)
	v_lshlrev_b32_e32 v36, 16, v148
	v_and_b32_e32 v37, 0xffff0000, v148
	v_pk_add_f32 v[54:55], v[54:55], v[110:111] op_sel_hi:[1,0]
	v_pk_add_f32 v[52:53], v[52:53], v[110:111] op_sel_hi:[1,0]
	v_lshlrev_b32_e32 v162, 16, v146
	v_and_b32_e32 v163, 0xffff0000, v146
	v_lshlrev_b32_e32 v146, 16, v147
	v_and_b32_e32 v147, 0xffff0000, v147
	v_pk_add_f32 v[34:35], v[34:35], v[110:111] op_sel_hi:[1,0]
	v_pk_mul_f32 v[32:33], v[32:33], v[36:37]
	v_lshlrev_b32_e32 v36, 16, v149
	v_and_b32_e32 v37, 0xffff0000, v149
	v_pk_mul_f32 v[52:53], v[52:53], v[162:163]
	v_pk_mul_f32 v[54:55], v[54:55], v[146:147]
	v_pk_mul_f32 v[34:35], v[34:35], v[36:37]
	v_cvt_pk_bf16_f32 v48, v52, v53
	v_cvt_pk_bf16_f32 v49, v54, v55
	v_cvt_pk_bf16_f32 v32, v32, v33
	v_cvt_pk_bf16_f32 v33, v34, v35
	global_store_dwordx2 v[132:133], v[48:49], off offset:64
	global_store_dwordx2 v[132:133], v[32:33], off offset:96
	s_or_b64 exec, exec, s[26:27]
	s_and_saveexec_b64 s[26:27], s[24:25]
	s_cbranch_execz .LBB0_743
	s_branch .LBB0_801

.LBB0_801:
	v_mov_b32_e32 v32, v201
	v_lshl_add_u64 v[34:35], s[42:43], 0, v[108:109]
	v_mov_b32_e32 v36, v218
	v_mov_b32_e32 v37, v219
	v_mov_b32_e32 v38, v220
	v_mov_b32_e32 v39, v221
	v_mov_b32_e32 v40, v222
	v_mov_b32_e32 v41, v223
	v_mov_b32_e32 v42, v224
	v_mov_b32_e32 v43, v225
	v_mov_b32_e32 v44, v226
	v_mov_b32_e32 v45, v227
	v_mov_b32_e32 v46, v228
	v_mov_b32_e32 v47, v229
	v_mov_b32_e32 v48, v230
	v_mov_b32_e32 v49, v231
	v_mov_b32_e32 v50, v232
	v_mov_b32_e32 v51, v233
	v_lshlrev_b32_e32 v52, 16, v36
	v_and_b32_e32 v53, 0xffff0000, v36
	v_lshlrev_b32_e32 v36, 16, v37
	v_and_b32_e32 v37, 0xffff0000, v37
	v_lshlrev_b32_e32 v54, 16, v38
	v_pk_add_f32 v[30:31], v[30:31], v[32:33] op_sel_hi:[1,0]
	v_pk_add_f32 v[28:29], v[28:29], v[32:33] op_sel_hi:[1,0]
	v_pk_add_f32 v[6:7], v[6:7], v[32:33] op_sel_hi:[1,0]
	v_pk_add_f32 v[4:5], v[4:5], v[32:33] op_sel_hi:[1,0]
	v_lshlrev_b32_e32 v110, 16, v48
	v_and_b32_e32 v111, 0xffff0000, v48
	v_lshlrev_b32_e32 v48, 16, v49
	v_and_b32_e32 v49, 0xffff0000, v49
	v_pk_add_f32 v[26:27], v[26:27], v[32:33] op_sel_hi:[1,0]
	v_pk_add_f32 v[24:25], v[24:25], v[32:33] op_sel_hi:[1,0]
	v_pk_add_f32 v[22:23], v[22:23], v[32:33] op_sel_hi:[1,0]
	v_pk_add_f32 v[20:21], v[20:21], v[32:33] op_sel_hi:[1,0]
	v_pk_add_f32 v[18:19], v[18:19], v[32:33] op_sel_hi:[1,0]
	v_pk_add_f32 v[16:17], v[16:17], v[32:33] op_sel_hi:[1,0]
	v_pk_add_f32 v[14:15], v[14:15], v[32:33] op_sel_hi:[1,0]
	v_pk_add_f32 v[12:13], v[12:13], v[32:33] op_sel_hi:[1,0]
	v_pk_add_f32 v[10:11], v[10:11], v[32:33] op_sel_hi:[1,0]
	v_pk_add_f32 v[8:9], v[8:9], v[32:33] op_sel_hi:[1,0]
	v_and_b32_e32 v55, 0xffff0000, v38
	v_lshlrev_b32_e32 v38, 16, v39
	v_and_b32_e32 v39, 0xffff0000, v39
	v_lshlrev_b32_e32 v56, 16, v40
	v_and_b32_e32 v57, 0xffff0000, v40
	v_lshlrev_b32_e32 v40, 16, v41
	v_and_b32_e32 v41, 0xffff0000, v41
	v_lshlrev_b32_e32 v58, 16, v42
	v_and_b32_e32 v59, 0xffff0000, v42
	v_lshlrev_b32_e32 v42, 16, v43
	v_and_b32_e32 v43, 0xffff0000, v43
	v_lshlrev_b32_e32 v60, 16, v44
	v_and_b32_e32 v61, 0xffff0000, v44
	v_lshlrev_b32_e32 v44, 16, v45
	v_and_b32_e32 v45, 0xffff0000, v45
	v_lshlrev_b32_e32 v62, 16, v46
	v_and_b32_e32 v63, 0xffff0000, v46
	v_lshlrev_b32_e32 v46, 16, v47
	v_and_b32_e32 v47, 0xffff0000, v47
	v_pk_mul_f32 v[28:29], v[28:29], v[52:53]
	v_pk_mul_f32 v[30:31], v[30:31], v[36:37]
	v_pk_mul_f32 v[4:5], v[4:5], v[110:111]
	v_pk_mul_f32 v[6:7], v[6:7], v[48:49]
	v_pk_mul_f32 v[24:25], v[24:25], v[54:55]
	v_pk_mul_f32 v[26:27], v[26:27], v[38:39]
	v_pk_mul_f32 v[20:21], v[20:21], v[56:57]
	v_pk_mul_f32 v[22:23], v[22:23], v[40:41]
	v_pk_mul_f32 v[16:17], v[16:17], v[58:59]
	v_pk_mul_f32 v[18:19], v[18:19], v[42:43]
	v_pk_mul_f32 v[12:13], v[12:13], v[60:61]
	v_pk_mul_f32 v[14:15], v[14:15], v[44:45]
	v_pk_mul_f32 v[8:9], v[8:9], v[62:63]
	v_pk_mul_f32 v[10:11], v[10:11], v[46:47]
	v_cvt_pk_bf16_f32 v28, v28, v29
	v_cvt_pk_bf16_f32 v29, v30, v31
	v_cvt_pk_bf16_f32 v4, v4, v5
	v_cvt_pk_bf16_f32 v5, v6, v7
	v_cvt_pk_bf16_f32 v24, v24, v25
	v_cvt_pk_bf16_f32 v25, v26, v27
	v_cvt_pk_bf16_f32 v20, v20, v21
	v_cvt_pk_bf16_f32 v21, v22, v23
	v_cvt_pk_bf16_f32 v16, v16, v17
	v_cvt_pk_bf16_f32 v17, v18, v19
	v_cvt_pk_bf16_f32 v12, v12, v13
	v_cvt_pk_bf16_f32 v13, v14, v15
	v_cvt_pk_bf16_f32 v8, v8, v9
	v_cvt_pk_bf16_f32 v9, v10, v11
	global_store_dwordx2 v[34:35], v[28:29], off offset:-128
	global_store_dwordx2 v[34:35], v[24:25], off offset:-96
	global_store_dwordx2 v[34:35], v[20:21], off offset:-64
	global_store_dwordx2 v[34:35], v[16:17], off offset:-32
	global_store_dwordx2 v[34:35], v[12:13], off
	global_store_dwordx2 v[34:35], v[8:9], off offset:32
	global_store_dwordx2 v[34:35], v[4:5], off offset:64
	v_pk_add_f32 v[0:1], v[0:1], v[32:33] op_sel_hi:[1,0]
	v_lshlrev_b32_e32 v4, 16, v50
	v_and_b32_e32 v5, 0xffff0000, v50
	v_pk_add_f32 v[2:3], v[2:3], v[32:33] op_sel_hi:[1,0]
	v_pk_mul_f32 v[0:1], v[0:1], v[4:5]
	v_lshlrev_b32_e32 v4, 16, v51
	v_and_b32_e32 v5, 0xffff0000, v51
	v_pk_mul_f32 v[2:3], v[2:3], v[4:5]
	v_cvt_pk_bf16_f32 v0, v0, v1
	v_cvt_pk_bf16_f32 v1, v2, v3
	global_store_dwordx2 v[34:35], v[0:1], off offset:96
	s_branch .LBB0_743
